# gatef rows on the 7 fully row-less blocks 249..255 (block 248 still has 4 waves of rows); otherwise v74
# baseline (speedup 1.0000x reference)
; __device__ __forceinline__ void phase1(const Args& a, LAS unsigned char* L) {
;     ...
;     for (int r = bid; r < 48; r += G)
;         for (int c = tid; c < DM; c += 512) { float s = bada[2048 + c];
; #pragma unroll
;             for (int q = 0; q < 4; ++q) s += modp[(size_t)(q * 48 + r) * 3072 + 2048 + c];
;             gatef[r * DM + c] = s; }
.LBB0_101:
	s_or_b64 exec, exec, s[0:1]
	s_add_u32 s22, s28, 0x1e400000
	s_waitcnt lgkmcnt(0)
	v_mov_b32_e32 v0, v180
	s_addc_u32 s23, s29, 0
	s_barrier
	s_cmp_lt_i32 s2, 0xf9
	v_readfirstlane_b32 s12, v0
	s_cbranch_scc1 .LBB0_107
	s_mov_b32 s98, s2
	s_mov_b32 s99, s30
	s_sub_i32 s2, s2, 0xf9
	s_mov_b32 s30, 7
	v_ashrrev_i32_e32 v1, 31, v0
	s_movk_i32 s0, 0x400
	v_lshlrev_b64 v[8:9], 2, v[0:1]
	v_cmp_gt_i32_e32 vcc, s0, v0
	v_lshl_add_u64 v[4:5], s[54:55], 0, v[8:9]
	s_mov_b64 s[0:1], 0x2000
	s_lshl_b32 s13, s30, 10
	v_lshl_add_u64 v[4:5], v[4:5], 0, s[0:1]
	s_mul_i32 s0, s2, 0x3000
	s_mul_hi_i32 s1, s2, 0x3000
	s_add_u32 s0, s28, s0
	s_addc_u32 s1, s29, s1
	v_lshl_add_u64 v[6:7], s[0:1], 0, v[8:9]
	s_mov_b64 s[0:1], 0x1e102000
	v_lshl_add_u64 v[8:9], s[28:29], 0, v[8:9]
	v_add_u32_e32 v18, 0xfffffe00, v0
	v_lshl_add_u32 v2, s2, 10, v0
	v_lshl_add_u64 v[6:7], v[6:7], 0, s[0:1]
	s_mul_hi_i32 s5, s30, 0x3000
	s_mul_i32 s4, s30, 0x3000
	v_lshl_add_u64 v[8:9], v[8:9], 0, s[0:1]
	s_add_i32 s14, s2, 48
	s_add_i32 s15, s2, 0x60
	s_add_i32 s16, s2, 0x90
	s_movk_i32 s17, 0x1ff
	v_mov_b32_e32 v1, 0x3000
	s_mov_b32 s33, s2
	s_branch .LBB0_104
